# attention softmax: 14 scalar subtracts packed into 7 v_pk_add, serial 16-add row-sum replaced by packed tree (8 instr); on top of 288-B stride version
# speedup vs baseline: 1.0069x; 1.0069x over previous
; __device__ __forceinline__ unsigned cvt_pk_bf16(float lo, float hi) { unsigned r; asm("v_cvt_pk_bf16_f32 %0, %1, %2" : "=v"(r) : "v"(lo), "v"(hi)); return r; }
; #define LAS __attribute__((address_space(3)))
; #define MFMA16(a, b, c) __builtin_amdgcn_mfma_f32_16x16x32_bf16((a), (b), (c), 0, 0, 0)
; #define ATT_STORE(buf_) do { _Pragma("unroll") for (int i = 0; i < 8; ++i) \
;     *(LAS u32x4*)(st0 + (buf_) * ATT_BUF + ((i >> 2) * 2 + ((i >> 1) & 1)) * ATT_TILE + (i & 1) * 32 * 272) = t[i]; } while (0)
; __device__ __forceinline__ void attn_wg_item(const Params& p, int item, LAS unsigned char* lds) {
;     ...
;     tmax = fmaxf(tmax, __shfl_xor(tmax, 16)); tmax = fmaxf(tmax, __shfl_xor(tmax, 32));
;     const float mnew = fmaxf(mrun, tmax), alpha = __builtin_amdgcn_exp2f(mrun - mnew); mrun = mnew;
;     float psum = 0.f;
; #pragma unroll
;     for (int kt = 0; kt < 4; ++kt)
; #pragma unroll
;       for (int i = 0; i < 4; ++i) { const float e = __builtin_amdgcn_exp2f(S[kt][i] - mnew); S[kt][i] = e; psum += e; }
;     lsum = lsum * alpha + psum;
; #pragma unroll
;     for (int dt = 0; dt < 8; ++dt) O[dt] *= alpha;
;     bf16x8 Pf[2];
; #pragma unroll
;     for (int s2 = 0; s2 < 2; ++s2) { u32x4 wv; wv.x = cvt_pk_bf16(S[2 * s2][0], S[2 * s2][1]); wv.y = cvt_pk_bf16(S[2 * s2][2], S[2 * s2][3]);
;       wv.z = cvt_pk_bf16(S[2 * s2 + 1][0], S[2 * s2 + 1][1]); wv.w = cvt_pk_bf16(S[2 * s2 + 1][2], S[2 * s2 + 1][3]); Pf[s2] = __builtin_bit_cast(bf16x8, wv); }
;     { const int qq = l15 >> 2, pp = l15 & 3; LAS unsigned char* vb = Vl + (4 * kq + qq) * 272 + pp * 8;
; #pragma unroll
;       for (int s2 = 0; s2 < 2; ++s2)
; #pragma unroll
;         for (int dt = 0; dt < 8; ++dt) {
;           const s16x4 lo = __builtin_amdgcn_ds_read_tr16_b64_v4i16((LAS s16x4*)(vb + (32 * s2) * 272 + dt * 32));
;           const s16x4 hi = __builtin_amdgcn_ds_read_tr16_b64_v4i16((LAS s16x4*)(vb + (32 * s2 + 16) * 272 + dt * 32));
;           const bf16x8 Vf = __builtin_shufflevector(lo, hi, 0, 1, 2, 3, 4, 5, 6, 7);
;           O[dt] = MFMA16(Vf, Pf[s2], O[dt]); } }
;     if (ps < 8) ATT_STORE((ps + 1) & 1);
.LBB0_822:
	s_or_b64 exec, exec, s[14:15]
	s_waitcnt lgkmcnt(0)
	s_nop 0
	v_add_f32_e32 v136, v83, v136
	v_max_f32_e32 v80, v158, v158
	v_max_f32_e32 v80, v80, v136
	s_andn2_b64 vcc, exec, s[10:11]
	v_mov_b32_e32 v81, v80
	v_mov_b32_e32 v166, v80
	s_nop 1
	v_permlane16_swap_b32_e32 v81, v166
	v_max_f32_e32 v80, v81, v166
	v_mov_b32_e32 v81, v80
	v_mov_b32_e32 v166, v80
	s_nop 1
	v_permlane32_swap_b32_e32 v81, v166
	v_max3_f32 v81, v155, v81, v166
	v_sub_f32_e32 v80, v155, v81
	v_pk_add_f32 v[82:83], v[122:123], v[80:81] op_sel:[0,1] op_sel_hi:[1,1] neg_lo:[0,1] neg_hi:[0,1]
	v_sub_f32_e32 v123, v136, v81
	v_add3_u32 v136, s16, v139, v140
	v_exp_f32_e32 v80, v80
	v_pk_add_f32 v[88:89], v[128:129], v[80:81] op_sel:[0,1] op_sel_hi:[1,1] neg_lo:[0,1] neg_hi:[0,1]
	v_pk_add_f32 v[90:91], v[130:131], v[80:81] op_sel:[0,1] op_sel_hi:[1,1] neg_lo:[0,1] neg_hi:[0,1]
	v_pk_add_f32 v[92:93], v[132:133], v[80:81] op_sel:[0,1] op_sel_hi:[1,1] neg_lo:[0,1] neg_hi:[0,1]
	v_pk_add_f32 v[94:95], v[134:135], v[80:81] op_sel:[0,1] op_sel_hi:[1,1] neg_lo:[0,1] neg_hi:[0,1]
	ds_read_b64_tr_b16 v[184:185], v136 offset:36864
	ds_read_b64_tr_b16 v[186:187], v136 offset:41472
	ds_read_b64_tr_b16 v[188:189], v136 offset:36896
	ds_read_b64_tr_b16 v[190:191], v136 offset:41504
	ds_read_b64_tr_b16 v[192:193], v136 offset:36928
	ds_read_b64_tr_b16 v[194:195], v136 offset:41536
	ds_read_b64_tr_b16 v[196:197], v136 offset:36960
	ds_read_b64_tr_b16 v[198:199], v136 offset:41568
	ds_read_b64_tr_b16 v[200:201], v136 offset:36992
	ds_read_b64_tr_b16 v[202:203], v136 offset:41600
	ds_read_b64_tr_b16 v[204:205], v136 offset:37024
	ds_read_b64_tr_b16 v[206:207], v136 offset:41632
	ds_read_b64_tr_b16 v[208:209], v136 offset:37056
	ds_read_b64_tr_b16 v[210:211], v136 offset:41664
	v_pk_add_f32 v[84:85], v[124:125], v[80:81] op_sel:[0,1] op_sel_hi:[1,1] neg_lo:[0,1] neg_hi:[0,1]
	v_pk_add_f32 v[86:87], v[126:127], v[80:81] op_sel:[0,1] op_sel_hi:[1,1] neg_lo:[0,1] neg_hi:[0,1]
	v_pk_mul_f32 v[78:79], v[78:79], v[80:81] op_sel_hi:[1,0]
	v_pk_mul_f32 v[76:77], v[76:77], v[80:81] op_sel_hi:[1,0]
	v_pk_mul_f32 v[74:75], v[74:75], v[80:81] op_sel_hi:[1,0]
	v_pk_mul_f32 v[72:73], v[72:73], v[80:81] op_sel_hi:[1,0]
	v_pk_mul_f32 v[70:71], v[70:71], v[80:81] op_sel_hi:[1,0]
	v_pk_mul_f32 v[68:69], v[68:69], v[80:81] op_sel_hi:[1,0]
	v_pk_mul_f32 v[66:67], v[66:67], v[80:81] op_sel_hi:[1,0]
	v_pk_mul_f32 v[64:65], v[64:65], v[80:81] op_sel_hi:[1,0]
	v_exp_f32_e32 v82, v82
	v_exp_f32_e32 v83, v83
	v_exp_f32_e32 v84, v84
	v_exp_f32_e32 v85, v85
	v_exp_f32_e32 v86, v86
	v_exp_f32_e32 v87, v87
	v_exp_f32_e32 v88, v88
	v_exp_f32_e32 v89, v89
	v_cvt_pk_bf16_f32 v124, v82, v83
	v_cvt_pk_bf16_f32 v125, v84, v85
	v_cvt_pk_bf16_f32 v126, v86, v87
	v_cvt_pk_bf16_f32 v127, v88, v89
	v_pk_mul_f32 v[62:63], v[62:63], v[80:81] op_sel_hi:[1,0]
	s_waitcnt lgkmcnt(12)
	v_mfma_f32_16x16x32_bf16 v[76:79], v[184:187], v[124:127], v[76:79]
	ds_read_b64_tr_b16 v[212:213], v136 offset:37088
	ds_read_b64_tr_b16 v[214:215], v136 offset:41696
	v_pk_mul_f32 v[60:61], v[60:61], v[80:81] op_sel_hi:[1,0]
	v_pk_mul_f32 v[58:59], v[58:59], v[80:81] op_sel_hi:[1,0]
	s_waitcnt lgkmcnt(12)
	v_mfma_f32_16x16x32_bf16 v[72:75], v[188:191], v[124:127], v[72:75]
	ds_read_b64_tr_b16 v[216:217], v136 offset:46080
	ds_read_b64_tr_b16 v[218:219], v136 offset:50688
	v_mul_f32_e64 v56, v56, v80
	v_mul_f32_e64 v57, v57, v80
	v_pk_mul_f32 v[38:39], v[38:39], v[80:81] op_sel_hi:[1,0]
	v_pk_mul_f32 v[36:37], v[36:37], v[80:81] op_sel_hi:[1,0]
	s_waitcnt lgkmcnt(12)
	v_mfma_f32_16x16x32_bf16 v[68:71], v[192:195], v[124:127], v[68:71]
	ds_read_b64_tr_b16 v[220:221], v136 offset:46112
	ds_read_b64_tr_b16 v[222:223], v136 offset:50720
	v_mul_f32_e64 v30, v30, v80
	v_mul_f32_e64 v31, v31, v80
	v_pk_mul_f32 v[28:29], v[28:29], v[80:81] op_sel_hi:[1,0]
	v_sub_f32_e32 v122, v157, v81
	s_waitcnt lgkmcnt(12)
	v_mfma_f32_16x16x32_bf16 v[64:67], v[196:199], v[124:127], v[64:67]
	ds_read_b64_tr_b16 v[224:225], v136 offset:46144
	ds_read_b64_tr_b16 v[226:227], v136 offset:50752
	v_exp_f32_e32 v90, v90
	v_exp_f32_e32 v91, v91
	s_waitcnt lgkmcnt(12)
	v_mfma_f32_16x16x32_bf16 v[60:63], v[200:203], v[124:127], v[60:63]
	ds_read_b64_tr_b16 v[228:229], v136 offset:46176
	ds_read_b64_tr_b16 v[230:231], v136 offset:50784
	v_exp_f32_e32 v92, v92
	v_exp_f32_e32 v93, v93
	v_exp_f32_e32 v94, v94
	s_waitcnt lgkmcnt(12)
	v_mfma_f32_16x16x32_bf16 v[56:59], v[204:207], v[124:127], v[56:59]
	ds_read_b64_tr_b16 v[232:233], v136 offset:46208
	ds_read_b64_tr_b16 v[234:235], v136 offset:50816
	v_exp_f32_e32 v95, v95
	v_exp_f32_e32 v122, v122
	s_waitcnt lgkmcnt(12)
	v_mfma_f32_16x16x32_bf16 v[36:39], v[208:211], v[124:127], v[36:39]
	ds_read_b64_tr_b16 v[236:237], v136 offset:46240
	ds_read_b64_tr_b16 v[238:239], v136 offset:50848
	v_exp_f32_e32 v123, v123
	v_cvt_pk_bf16_f32 v128, v90, v91
	v_cvt_pk_bf16_f32 v129, v92, v93
	s_waitcnt lgkmcnt(12)
	v_mfma_f32_16x16x32_bf16 v[28:31], v[212:215], v[124:127], v[28:31]
	ds_read_b64_tr_b16 v[240:241], v136 offset:46272
	ds_read_b64_tr_b16 v[242:243], v136 offset:50880
	v_cvt_pk_bf16_f32 v130, v94, v95
	v_cvt_pk_bf16_f32 v131, v122, v123
	s_nop 1
	s_waitcnt lgkmcnt(12)
	v_mfma_f32_16x16x32_bf16 v[76:79], v[216:219], v[128:131], v[76:79]
	ds_read_b64_tr_b16 v[172:173], v136 offset:46304
	ds_read_b64_tr_b16 v[174:175], v136 offset:50912
	s_waitcnt lgkmcnt(12)
	v_mfma_f32_16x16x32_bf16 v[72:75], v[220:223], v[128:131], v[72:75]
	s_waitcnt lgkmcnt(10)
	v_mfma_f32_16x16x32_bf16 v[68:71], v[224:227], v[128:131], v[68:71]
	s_waitcnt lgkmcnt(8)
	v_mfma_f32_16x16x32_bf16 v[64:67], v[228:231], v[128:131], v[64:67]
	s_waitcnt lgkmcnt(6)
	v_mfma_f32_16x16x32_bf16 v[60:63], v[232:235], v[128:131], v[60:63]
	s_waitcnt lgkmcnt(4)
	v_mfma_f32_16x16x32_bf16 v[56:59], v[236:239], v[128:131], v[56:59]
	s_waitcnt lgkmcnt(2)
	v_mfma_f32_16x16x32_bf16 v[36:39], v[240:243], v[128:131], v[36:39]
	s_waitcnt lgkmcnt(0)
	v_mfma_f32_16x16x32_bf16 v[28:31], v[172:175], v[128:131], v[28:31]
	s_cbranch_vccnz .LBB0_824
	s_andn2_b32 s10, 1, s8
	s_mul_i32 s10, s10, 0x12000
	v_add_u32_e32 v124, s10, v137
	s_waitcnt vmcnt(0)
	ds_write_b128 v124, v[0:3]
	ds_write_b128 v124, v[8:11] offset:9216
	ds_write_b128 v124, v[4:7] offset:18432
	ds_write_b128 v124, v[16:19] offset:27648
	ds_write_b128 v124, v[12:15] offset:36864
	ds_write_b128 v124, v[24:27] offset:46080
	ds_write_b128 v124, v[20:23] offset:55296
	ds_write_b128 v124, v[32:35] offset:64512
; #define ATT_STORE(buf_) do { _Pragma("unroll") for (int i = 0; i < 8; ++i) \
;     *(LAS u32x4*)(st0 + (buf_) * ATT_BUF + ((i >> 2) * 2 + ((i >> 1) & 1)) * ATT_TILE + (i & 1) * 32 * 272) = t[i]; } while (0)
; __device__ __forceinline__ void attn_wg_item(const Params& p, int item, LAS unsigned char* lds) {
;     ...
;       for (int i = 0; i < 4; ++i) { const float e = __builtin_amdgcn_exp2f(S[kt][i] - mnew); S[kt][i] = e; psum += e; }
;     lsum = lsum * alpha + psum;
;     ...
;     if (ps < 8) ATT_STORE((ps + 1) & 1);
;     __syncthreads();
;   }
.LBB0_824:
	v_pk_add_f32 v[82:83], v[82:83], v[84:85]
	v_pk_add_f32 v[86:87], v[86:87], v[88:89]
	v_pk_add_f32 v[90:91], v[90:91], v[92:93]
	v_pk_add_f32 v[94:95], v[94:95], v[122:123]
	v_pk_add_f32 v[82:83], v[82:83], v[86:87]
	v_pk_add_f32 v[90:91], v[90:91], v[94:95]
	v_pk_add_f32 v[82:83], v[82:83], v[90:91]
	v_add_f32_e32 v82, v82, v83
	s_add_i32 s10, s8, 1
	s_sub_i32 s9, s9, 64
	s_add_i32 s19, s19, 64
	v_fmac_f32_e32 v82, v153, v80
	v_add_u32_e32 v151, 64, v151
	v_lshl_add_u64 v[114:115], v[114:115], 0, s[0:1]
	v_lshl_add_u64 v[116:117], v[116:117], 0, s[0:1]
	v_lshl_add_u64 v[118:119], v[118:119], 0, s[0:1]
	s_cmp_gt_u32 s8, 7
	v_lshl_add_u64 v[120:121], v[120:121], 0, s[0:1]
	s_waitcnt lgkmcnt(0)
	s_barrier
	s_cbranch_scc1 .LBB0_826
	v_mov_b32_e32 v153, v82
	v_mov_b32_e32 v155, v81
	s_mov_b32 s8, s10
	s_cmp_lg_u32 s39, s9
	s_cselect_b64 s[10:11], -1, 0
	s_cmp_eq_u32 s39, s9
	s_cbranch_scc0 .LBB0_817
	s_branch .LBB0_818
